# attention steady loop: K/V tile DMA addresses from scalar running bases + invariant 32-bit lane offsets (six 64-bit VALU adds per step removed)
# speedup vs baseline: 1.0086x; 1.0055x over previous
; #define LAS __attribute__((address_space(3)))
; #define WAIT_BAR(N) asm volatile("s_waitcnt vmcnt(" #N ") lgkmcnt(0)\n\ts_barrier" ::: "memory")
; #define DMA_K(t, slot) glds16(ksrc + (long)(t) * KVBLK * KP, (unsigned)__builtin_amdgcn_readfirstlane(kdst + (slot)))
; #define DMA_V(t, slot) glds16(vsrc + (long)(t) * KVBLK * KP, (unsigned)__builtin_amdgcn_readfirstlane(vdst + (slot)))
; #define ROT() do { sl_prev = sl_cur; sl_cur = sl_next; sl_next = (sl_next == (NSLOT - 1) * SLOTB) ? 0 : sl_next + SLOTB; } while (0)
; template <int THRL, bool FIXM> __device__ __forceinline__ bool attn_unit(const h16* Qrows, const h16* __restrict__ Kh, const h16* __restrict__ Vh, const int NT, h16* Yrows, const h16* BZrows, char* shm, const int tid, const float mfix, ...
;     ...
;   f32x16 pA0, pA1, pB0, pB1;
;   int sl_prev = 0, sl_cur = 0, sl_next = SLOTB;
;     ...
;   if (!warm) { DMA_K(2, 2 * SLOTB); WAIT_BAR(3); }
;   else { asm volatile("s_waitcnt vmcnt(4) lgkmcnt(0)\n\ts_barrier" ::: "memory");
; #pragma unroll
;       for (int d0 = 0; d0 < 4; ++d0) qr[d0] = *(const LAS s16x8*)((lds_cptr)shm + LDS_QN + wid * 4096 + (2 * d0 + hi) * 512 + r32 * 16); }
;   qkt(pA0, pA1, Kbase, qr, negm, r32, hi); asm volatile("s_nop 15\n\ts_nop 7" : "+v"(pA0), "+v"(pA1));
;   START(pA0, pA1);
;   _Pragma("unroll") for (int r = 0; r < 16; ++r) pA1[r] = __builtin_amdgcn_exp2f(pA1[r]);
;   if (!warm) WAIT_BAR(0); else WAIT_BAR(4);
;   DMA_K(3, 0); DMA_V(1, SLOTB);
;   ROT();
;   kload8(kf, kp0 + sl_cur);
;   WAIT_BAR(2);
.LBB0_75:
	v_exp_f32_e32 v66, v0
	v_lshlrev_b32_e32 v0, 1, v247
	v_and_b32_e32 v232, 32, v0
	v_lshlrev_b32_e32 v240, 8, v248
	v_lshlrev_b32_e32 v0, 4, v247
	s_movk_i32 s2, 0xc0
	v_and_or_b32 v231, v0, s2, v240
	s_mov_b64 s[2:3], 0x6000
	v_exp_f32_e32 v67, v18
	v_exp_f32_e32 v68, v19
	v_lshl_add_u64 v[18:19], v[34:35], 0, s[2:3]
	s_mov_b32 s2, m0
	s_mov_b32 m0, s97
	s_nop 0
	global_load_lds_dwordx4 v[18:19], off
	s_mov_b32 m0, s2
	s_mov_b64 s[2:3], 0x2000
	v_lshl_add_u64 v[18:19], v[36:37], 0, s[2:3]
	s_add_i32 s2, s83, 0x2000
	s_mov_b32 s3, m0
	s_mov_b32 m0, s2
	s_nop 0
	global_load_lds_dwordx4 v[18:19], off
	s_mov_b32 m0, s3
	ds_read_b128 v[192:195], v219 offset:8192
	ds_read_b128 v[188:191], v219 offset:8704
	ds_read_b128 v[184:187], v219 offset:10240
	ds_read_b128 v[180:183], v219 offset:10752
	ds_read_b128 v[176:179], v219 offset:12288
	ds_read_b128 v[172:175], v219 offset:12800
	ds_read_b128 v[168:171], v219 offset:14336
	ds_read_b128 v[164:167], v219 offset:14848
	v_exp_f32_e32 v82, v38
	v_exp_f32_e32 v83, v39
	v_exp_f32_e32 v84, v40
	v_exp_f32_e32 v85, v41
	v_exp_f32_e32 v86, v42
	v_exp_f32_e32 v87, v43
	v_exp_f32_e32 v88, v44
	v_exp_f32_e32 v89, v45
	v_exp_f32_e32 v90, v46
	v_exp_f32_e32 v91, v47
	v_exp_f32_e32 v92, v48
	v_exp_f32_e32 v93, v49
	v_exp_f32_e32 v94, v50
	v_exp_f32_e32 v95, v51
	v_exp_f32_e32 v96, v52
	v_exp_f32_e32 v97, v33
	v_exp_f32_e32 v69, v20
	v_exp_f32_e32 v70, v21
	v_exp_f32_e32 v71, v22
	v_exp_f32_e32 v72, v23
	v_exp_f32_e32 v73, v24
	v_exp_f32_e32 v74, v25
	v_exp_f32_e32 v75, v26
	v_exp_f32_e32 v76, v27
	v_exp_f32_e32 v77, v28
	v_exp_f32_e32 v78, v29
	v_exp_f32_e32 v79, v30
	v_exp_f32_e32 v80, v31
	v_exp_f32_e32 v81, v32
	s_waitcnt vmcnt(2) lgkmcnt(0)
	s_barrier
	v_add_u32_e32 v0, s41, v232
	s_mov_b32 s45, 1
	v_add3_u32 v233, v0, v243, v231
	s_and_b64 vcc, exec, s[38:39]
	s_mov_b32 s44, 0
	s_cbranch_vccnz .LBB0_79
	v_and_b32_e32 v0, 3, v247
	s_lshl_b32 s24, s29, 5
	v_lshlrev_b32_e32 v0, 4, v0
	s_and_b32 s24, s24, 0x1800
	s_add_i32 s2, s19, s18
	v_lshl_add_u64 v[18:19], s[14:15], 1, v[0:1]
	v_lshl_or_b32 v0, v239, 7, s24
	s_lshl_b64 s[24:25], s[12:13], 1
	s_add_u32 s24, s22, s24
	v_lshl_add_u64 v[18:19], v[18:19], 0, v[0:1]
	v_mov_b32_e32 v215, v1
	s_addc_u32 s25, s23, s25
	v_mov_b32_e32 v50, 0
	s_mul_hi_u32 s3, s2, 0x48000
	s_mul_i32 s2, s2, 0x48000
	v_lshl_add_u64 v[54:55], s[22:23], 0, v[18:19]
	v_lshl_add_u64 v[56:57], s[24:25], 0, v[214:215]
	s_add_u32 s100, s24, s2
	s_addc_u32 s101, s25, s3
	s_add_u32 s100, s100, 0x10388000
	s_addc_u32 s101, s101, 0
	s_lshl_b64 vcc, s[14:15], 1
	s_add_u32 vcc_lo, vcc_lo, s22
	s_addc_u32 vcc_hi, vcc_hi, s23
	v_subrev_u32_e32 v208, vcc_lo, v54
	s_add_u32 vcc_lo, vcc_lo, s2
	s_addc_u32 vcc_hi, vcc_hi, s3
	s_add_u32 vcc_lo, vcc_lo, 0x10c84000
	s_addc_u32 vcc_hi, vcc_hi, 0
	s_movk_i32 s25, 0x4000
	s_movk_i32 s42, 0x2000
	s_mov_b32 s24, -1
	v_mov_b32_e32 v18, 0
	v_mov_b32_e32 v19, v50
	v_mov_b32_e32 v20, v50
	v_mov_b32_e32 v21, v50
	v_mov_b32_e32 v22, v50
	v_mov_b32_e32 v23, v50
	v_mov_b32_e32 v24, v50
	v_mov_b32_e32 v25, v50
	v_mov_b32_e32 v26, v50
	v_mov_b32_e32 v27, v50
	v_mov_b32_e32 v28, v50
	v_mov_b32_e32 v29, v50
	v_mov_b32_e32 v30, v50
	v_mov_b32_e32 v31, v50
	v_mov_b32_e32 v32, v50
	v_mov_b32_e32 v33, v50
	v_mov_b32_e32 v34, 0
	v_mov_b32_e32 v35, v50
	v_mov_b32_e32 v36, v50
	v_mov_b32_e32 v37, v50
	v_mov_b32_e32 v38, v50
	v_mov_b32_e32 v39, v50
	v_mov_b32_e32 v40, v50
	v_mov_b32_e32 v41, v50
	v_mov_b32_e32 v42, v50
	v_mov_b32_e32 v43, v50
	v_mov_b32_e32 v44, v50
	v_mov_b32_e32 v45, v50
	v_mov_b32_e32 v46, v50
	v_mov_b32_e32 v47, v50
	v_mov_b32_e32 v48, v50
	v_mov_b32_e32 v49, v50
	s_mov_b64 s[46:47], 0x10388000
	s_mov_b64 s[36:37], 0x10c84000
	s_mov_b64 s[48:49], 0x1038a000
	s_mov_b64 s[52:53], 0x10c86000
.LBB0_77:
	v_add_u32_e32 v0, s44, v233
	ds_read_b64_tr_b16 v[62:63], v0 offset:24576
	ds_read_b64_tr_b16 v[64:65], v0 offset:25088
	v_add_f32_e32 v51, v82, v83
	v_add_f32_e32 v51, v84, v51
	v_add_f32_e32 v51, v85, v51
	v_add_f32_e32 v51, v86, v51
	v_add_f32_e32 v51, v87, v51
	v_cvt_pk_f16_f32 v160, v82, v83
	v_cvt_pk_f16_f32 v161, v84, v85
	s_waitcnt lgkmcnt(9)
	v_mfma_f32_32x32x16_f16 v[114:129], v[192:195], v[144:147], v[2:17]
	ds_read_b64_tr_b16 v[82:83], v0 offset:28672
	ds_read_b64_tr_b16 v[84:85], v0 offset:29184
	v_add_f32_e32 v51, v88, v51
	v_add_f32_e32 v51, v89, v51
	v_add_f32_e32 v51, v90, v51
	v_add_f32_e32 v51, v91, v51
	v_cvt_pk_f16_f32 v162, v86, v87
	v_cvt_pk_f16_f32 v163, v88, v89
	s_waitcnt lgkmcnt(10)
	v_mfma_f32_32x32x16_f16 v[98:113], v[188:191], v[144:147], v[2:17]
	ds_read_b64_tr_b16 v[86:87], v0 offset:25600
	ds_read_b64_tr_b16 v[88:89], v0 offset:26112
	v_add_f32_e32 v51, v92, v51
	v_add_f32_e32 v51, v93, v51
	v_add_f32_e32 v51, v94, v51
	v_add_f32_e32 v51, v95, v51
	v_cvt_pk_f16_f32 v156, v90, v91
	v_cvt_pk_f16_f32 v157, v92, v93
	s_waitcnt lgkmcnt(11)
	v_mfma_f32_32x32x16_f16 v[114:129], v[184:187], v[140:143], v[114:129]
	ds_read_b64_tr_b16 v[90:91], v0 offset:29696
	ds_read_b64_tr_b16 v[92:93], v0 offset:30208
	v_add_f32_e32 v51, v96, v51
	v_add_f32_e32 v51, v97, v51
	v_add_f32_e32 v51, v66, v51
	v_add_f32_e32 v51, v67, v51
	v_cvt_pk_f16_f32 v158, v94, v95
	v_cvt_pk_f16_f32 v159, v96, v97
	s_waitcnt lgkmcnt(12)
	v_mfma_f32_32x32x16_f16 v[98:113], v[180:183], v[140:143], v[98:113]
	ds_read_b64_tr_b16 v[94:95], v0 offset:26624
	ds_read_b64_tr_b16 v[96:97], v0 offset:27136
	v_add_f32_e32 v51, v68, v51
	v_add_f32_e32 v51, v69, v51
	v_add_f32_e32 v51, v70, v51
	v_add_f32_e32 v51, v71, v51
	v_cvt_pk_f16_f32 v152, v66, v67
	v_cvt_pk_f16_f32 v153, v68, v69
	s_waitcnt lgkmcnt(13)
	v_mfma_f32_32x32x16_f16 v[114:129], v[176:179], v[136:139], v[114:129]
	ds_read_b64_tr_b16 v[66:67], v0 offset:30720
	ds_read_b64_tr_b16 v[68:69], v0 offset:31232
	v_add_f32_e32 v51, v72, v51
	v_add_f32_e32 v51, v73, v51
	v_add_f32_e32 v51, v74, v51
	v_add_f32_e32 v51, v75, v51
	v_cvt_pk_f16_f32 v154, v70, v71
	v_cvt_pk_f16_f32 v155, v72, v73
	s_waitcnt lgkmcnt(14)
	v_mfma_f32_32x32x16_f16 v[98:113], v[172:175], v[136:139], v[98:113]
	ds_read_b64_tr_b16 v[70:71], v0 offset:27648
	ds_read_b64_tr_b16 v[72:73], v0 offset:28160
	v_add_f32_e32 v51, v76, v51
	v_add_f32_e32 v51, v77, v51
	v_add_f32_e32 v51, v78, v51
	v_add_f32_e32 v51, v79, v51
	v_cvt_pk_f16_f32 v148, v74, v75
	v_cvt_pk_f16_f32 v149, v76, v77
	s_waitcnt lgkmcnt(14)
	v_mfma_f32_32x32x16_f16 v[114:129], v[168:171], v[132:135], v[114:129]
	ds_read_b64_tr_b16 v[74:75], v0 offset:31744
	ds_read_b64_tr_b16 v[76:77], v0 offset:32256
	v_add_f32_e32 v0, v80, v51
	v_add_f32_e32 v0, v81, v0
	v_add_f32_e32 v0, 0, v0
	v_cvt_pk_f16_f32 v150, v78, v79
	v_cvt_pk_f16_f32 v151, v80, v81
	v_mfma_f32_32x32x16_f16 v[98:113], v[164:167], v[132:135], v[98:113]
	v_add_f32_e32 v0, v50, v0
	s_add_i32 s43, s42, s97
	s_mov_b32 s44, m0
	s_mov_b32 m0, s43
	s_nop 0
	global_load_lds_dwordx4 v214, s[100:101]
	s_mov_b32 m0, s44
	s_add_i32 s43, s25, s83
	s_mov_b32 s44, m0
	s_mov_b32 m0, s43
	s_nop 0
	global_load_lds_dwordx4 v208, vcc
	s_mov_b32 m0, s44
	s_add_u32 s100, s100, 0x2000
	s_addc_u32 s101, s101, 0
	s_add_u32 vcc_lo, vcc_lo, 0x2000
	s_addc_u32 vcc_hi, vcc_hi, 0
	s_waitcnt lgkmcnt(14)
	v_mfma_f32_32x32x16_f16 v[18:33], v[160:163], v[62:65], v[18:33]
	v_exp_f32_e32 v114, v114
	v_exp_f32_e32 v115, v115
	v_exp_f32_e32 v116, v116
	v_exp_f32_e32 v117, v117
	s_waitcnt lgkmcnt(12)
	v_mfma_f32_32x32x16_f16 v[34:49], v[160:163], v[82:85], v[34:49]
	v_exp_f32_e32 v118, v118
	v_exp_f32_e32 v119, v119
	v_exp_f32_e32 v120, v120
	v_exp_f32_e32 v121, v121
	v_add_u32_e32 v50, s25, v219
	ds_read_b128 v[62:65], v50
	ds_read_b128 v[164:167], v50 offset:512
	s_waitcnt lgkmcnt(12)
	v_mfma_f32_32x32x16_f16 v[18:33], v[156:159], v[86:89], v[18:33]
	v_exp_f32_e32 v122, v122
	v_exp_f32_e32 v123, v123
	v_exp_f32_e32 v124, v124
	v_exp_f32_e32 v125, v125
	ds_read_b128 v[168:171], v50 offset:2048
	ds_read_b128 v[172:175], v50 offset:2560
	s_waitcnt lgkmcnt(12)
	v_mfma_f32_32x32x16_f16 v[34:49], v[156:159], v[90:93], v[34:49]
	v_exp_f32_e32 v126, v126
	v_exp_f32_e32 v127, v127
	v_exp_f32_e32 v128, v128
	v_exp_f32_e32 v129, v129
	ds_read_b128 v[176:179], v50 offset:4096
	ds_read_b128 v[180:183], v50 offset:4608
	s_waitcnt lgkmcnt(12)
	v_mfma_f32_32x32x16_f16 v[18:33], v[152:155], v[94:97], v[18:33]
	v_exp_f32_e32 v98, v98
	v_exp_f32_e32 v99, v99
	v_exp_f32_e32 v100, v100
	v_exp_f32_e32 v101, v101
	ds_read_b128 v[184:187], v50 offset:6144
	ds_read_b128 v[50:53], v50 offset:6656
	s_waitcnt lgkmcnt(12)
	v_mfma_f32_32x32x16_f16 v[34:49], v[152:155], v[66:69], v[34:49]
	v_exp_f32_e32 v102, v102
	v_exp_f32_e32 v103, v103
	v_exp_f32_e32 v104, v104
	v_exp_f32_e32 v105, v105
	s_waitcnt lgkmcnt(10)
	v_mfma_f32_32x32x16_f16 v[18:33], v[148:151], v[70:73], v[18:33]
	v_exp_f32_e32 v106, v106
	v_exp_f32_e32 v107, v107
	v_exp_f32_e32 v108, v108
	v_exp_f32_e32 v109, v109
	s_waitcnt lgkmcnt(8)
	v_mfma_f32_32x32x16_f16 v[34:49], v[148:151], v[74:77], v[34:49]
	v_exp_f32_e32 v110, v110
	v_exp_f32_e32 v111, v111
	v_exp_f32_e32 v112, v112
	v_exp_f32_e32 v113, v113
	s_waitcnt vmcnt(2) lgkmcnt(8)
	s_barrier
; #define WAIT_BAR(N) asm volatile("s_waitcnt vmcnt(" #N ") lgkmcnt(0)\n\ts_barrier" ::: "memory")
; #define RESC() do { if (!FIXM && resc) { asm volatile("s_waitcnt lgkmcnt(0)" ::: "memory"); \
;       _Pragma("unroll") for (int d_ = 0; d_ < 2; ++d_) _Pragma("unroll") for (int r = 0; r < 16; ++r) o[d_][r] *= wsf[crow(r, hi)]; } } while (0)
; #define ROT() do { sl_prev = sl_cur; sl_cur = sl_next; sl_next = (sl_next == (NSLOT - 1) * SLOTB) ? 0 : sl_next + SLOTB; } while (0)
; template <int THRL, bool FIXM> __device__ __forceinline__ bool attn_unit(const h16* Qrows, const h16* __restrict__ Kh, const h16* __restrict__ Vh, const int NT, h16* Yrows, const h16* BZrows, char* shm, const int tid, const float mfix, ...
;     ...
;   int t = 1;
;   for (; t + 5 < NT; t += 2) {
;     STEP(pB0, pB1, pA0, pA1, t, true, true, true);     WAIT_BAR(2); RESC(); ROT();
;     STEP(pA0, pA1, pB0, pB1, t + 1, true, true, true); WAIT_BAR(2); RESC(); ROT();
	s_add_i32 s43, s25, 0x2000
	s_cmpk_lg_i32 s25, 0x4000
	s_cselect_b32 s43, s43, 0
	v_add_u32_e32 v192, s42, v233
	ds_read_b64_tr_b16 v[188:189], v192 offset:24576
	ds_read_b64_tr_b16 v[190:191], v192 offset:25088
	s_waitcnt lgkmcnt(9)
	v_mfma_f32_32x32x16_f16 v[82:97], v[62:65], v[144:147], v[2:17]
	v_add_f32_e32 v66, v114, v115
	v_add_f32_e32 v66, v116, v66
	v_add_f32_e32 v66, v117, v66
	v_add_f32_e32 v66, v118, v66
	v_add_f32_e32 v66, v119, v66
	v_cvt_pk_f16_f32 v160, v114, v115
	v_cvt_pk_f16_f32 v161, v116, v117
	ds_read_b64_tr_b16 v[62:63], v192 offset:28672
	ds_read_b64_tr_b16 v[64:65], v192 offset:29184
	v_add_f32_e32 v66, v120, v66
	v_add_f32_e32 v66, v121, v66
	v_add_f32_e32 v66, v122, v66
	v_add_f32_e32 v148, v123, v66
	s_waitcnt lgkmcnt(10)
	v_mfma_f32_32x32x16_f16 v[66:81], v[164:167], v[144:147], v[2:17]
	v_cvt_pk_f16_f32 v162, v118, v119
	v_cvt_pk_f16_f32 v163, v120, v121
	ds_read_b64_tr_b16 v[114:115], v192 offset:25600
	ds_read_b64_tr_b16 v[116:117], v192 offset:26112
	s_waitcnt lgkmcnt(11)
	v_mfma_f32_32x32x16_f16 v[82:97], v[168:171], v[140:143], v[82:97]
	v_add_f32_e32 v118, v124, v148
	v_add_f32_e32 v118, v125, v118
	v_add_f32_e32 v118, v126, v118
	v_add_f32_e32 v148, v127, v118
	v_cvt_pk_f16_f32 v156, v122, v123
	v_cvt_pk_f16_f32 v157, v124, v125
	ds_read_b64_tr_b16 v[118:119], v192 offset:29696
	ds_read_b64_tr_b16 v[120:121], v192 offset:30208
	s_waitcnt lgkmcnt(12)
	v_mfma_f32_32x32x16_f16 v[66:81], v[172:175], v[140:143], v[66:81]
	v_add_f32_e32 v122, v128, v148
	v_add_f32_e32 v122, v129, v122
	v_add_f32_e32 v122, v98, v122
	v_add_f32_e32 v148, v99, v122
	v_cvt_pk_f16_f32 v158, v126, v127
	v_cvt_pk_f16_f32 v159, v128, v129
	ds_read_b64_tr_b16 v[122:123], v192 offset:26624
	ds_read_b64_tr_b16 v[124:125], v192 offset:27136
	s_waitcnt lgkmcnt(13)
	v_mfma_f32_32x32x16_f16 v[82:97], v[176:179], v[136:139], v[82:97]
	v_add_f32_e32 v126, v100, v148
	v_add_f32_e32 v126, v101, v126
	v_add_f32_e32 v126, v102, v126
	v_add_f32_e32 v126, v103, v126
	v_cvt_pk_f16_f32 v152, v98, v99
	v_cvt_pk_f16_f32 v153, v100, v101
	ds_read_b64_tr_b16 v[98:99], v192 offset:30720
	ds_read_b64_tr_b16 v[100:101], v192 offset:31232
	s_waitcnt lgkmcnt(14)
	v_mfma_f32_32x32x16_f16 v[66:81], v[180:183], v[136:139], v[66:81]
	v_add_f32_e32 v126, v104, v126
	v_add_f32_e32 v126, v105, v126
	v_add_f32_e32 v126, v106, v126
	v_add_f32_e32 v126, v107, v126
	v_cvt_pk_f16_f32 v154, v102, v103
	v_cvt_pk_f16_f32 v155, v104, v105
	ds_read_b64_tr_b16 v[102:103], v192 offset:27648
	ds_read_b64_tr_b16 v[104:105], v192 offset:28160
	s_waitcnt lgkmcnt(14)
	v_mfma_f32_32x32x16_f16 v[82:97], v[184:187], v[132:135], v[82:97]
	v_add_f32_e32 v126, v108, v126
	v_add_f32_e32 v126, v109, v126
	v_add_f32_e32 v126, v110, v126
	v_add_f32_e32 v126, v111, v126
	v_cvt_pk_f16_f32 v148, v106, v107
	v_cvt_pk_f16_f32 v149, v108, v109
	ds_read_b64_tr_b16 v[106:107], v192 offset:31744
	ds_read_b64_tr_b16 v[108:109], v192 offset:32256
	v_mfma_f32_32x32x16_f16 v[66:81], v[50:53], v[132:135], v[66:81]
	v_add_f32_e32 v50, v112, v126
	v_add_f32_e32 v50, v113, v50
	v_add_f32_e32 v50, 0, v50
	v_cvt_pk_f16_f32 v150, v110, v111
	v_cvt_pk_f16_f32 v151, v112, v113
	s_add_i32 s42, s25, s97
	s_mov_b32 s44, m0
	s_mov_b32 m0, s42
	s_nop 0
	global_load_lds_dwordx4 v214, s[100:101]
	s_mov_b32 m0, s44
	s_add_i32 s42, s43, s83
	s_mov_b32 s44, m0
	s_mov_b32 m0, s42
	s_nop 0
	global_load_lds_dwordx4 v208, vcc
	s_mov_b32 m0, s44
	s_add_u32 s100, s100, 0x2000
	s_addc_u32 s101, s101, 0
	s_add_u32 vcc_lo, vcc_lo, 0x2000
	s_addc_u32 vcc_hi, vcc_hi, 0
	v_add_f32_e32 v50, v0, v50
	s_waitcnt lgkmcnt(14)
	v_mfma_f32_32x32x16_f16 v[18:33], v[160:163], v[188:191], v[18:33]
	v_exp_f32_e32 v82, v82
	v_exp_f32_e32 v83, v83
	v_exp_f32_e32 v84, v84
	v_exp_f32_e32 v85, v85
	s_waitcnt lgkmcnt(12)
	v_mfma_f32_32x32x16_f16 v[34:49], v[160:163], v[62:65], v[34:49]
	v_exp_f32_e32 v86, v86
	v_exp_f32_e32 v87, v87
	v_exp_f32_e32 v88, v88
	v_exp_f32_e32 v89, v89
	v_add_u32_e32 v0, s43, v219
	ds_read_b128 v[192:195], v0
	ds_read_b128 v[188:191], v0 offset:512
	s_waitcnt lgkmcnt(12)
	v_mfma_f32_32x32x16_f16 v[18:33], v[156:159], v[114:117], v[18:33]
	v_exp_f32_e32 v90, v90
	v_exp_f32_e32 v91, v91
	v_exp_f32_e32 v92, v92
	v_exp_f32_e32 v93, v93
	ds_read_b128 v[184:187], v0 offset:2048
	ds_read_b128 v[180:183], v0 offset:2560
	s_waitcnt lgkmcnt(12)
	v_mfma_f32_32x32x16_f16 v[34:49], v[156:159], v[118:121], v[34:49]
	v_exp_f32_e32 v94, v94
	v_exp_f32_e32 v95, v95
	v_exp_f32_e32 v96, v96
	v_exp_f32_e32 v97, v97
	ds_read_b128 v[176:179], v0 offset:4096
	ds_read_b128 v[172:175], v0 offset:4608
	s_waitcnt lgkmcnt(12)
	v_mfma_f32_32x32x16_f16 v[18:33], v[152:155], v[122:125], v[18:33]
	v_exp_f32_e32 v66, v66
	v_exp_f32_e32 v67, v67
	v_exp_f32_e32 v68, v68
	v_exp_f32_e32 v69, v69
	ds_read_b128 v[168:171], v0 offset:6144
	ds_read_b128 v[164:167], v0 offset:6656
	s_waitcnt lgkmcnt(12)
	v_mfma_f32_32x32x16_f16 v[34:49], v[152:155], v[98:101], v[34:49]
	v_exp_f32_e32 v70, v70
	v_exp_f32_e32 v71, v71
	v_exp_f32_e32 v72, v72
	v_exp_f32_e32 v73, v73
	s_waitcnt lgkmcnt(10)
	v_mfma_f32_32x32x16_f16 v[18:33], v[148:151], v[102:105], v[18:33]
	v_exp_f32_e32 v74, v74
	v_exp_f32_e32 v75, v75
	v_exp_f32_e32 v76, v76
	v_exp_f32_e32 v77, v77
	s_waitcnt lgkmcnt(8)
	v_mfma_f32_32x32x16_f16 v[34:49], v[148:151], v[106:109], v[34:49]
	v_exp_f32_e32 v78, v78
	v_exp_f32_e32 v79, v79
	v_exp_f32_e32 v80, v80
	v_exp_f32_e32 v81, v81
	s_add_i32 s45, s43, 0x2000
	s_waitcnt vmcnt(2) lgkmcnt(8)
	s_barrier
	s_cmpk_lg_i32 s43, 0x4000
	s_mov_b32 s44, s25
	s_cselect_b32 s25, s45, 0
	s_add_i32 s24, s24, 2
	v_lshl_add_u64 v[54:55], v[54:55], 0, s[62:63]
	v_lshl_add_u64 v[56:57], v[56:57], 0, s[62:63]
	s_mov_b32 s42, s43
	s_cmp_lt_u32 s24, 29
	s_cbranch_scc1 .LBB0_77
	s_mov_b64 s[36:37], 0x10c84000
	s_mov_b64 s[60:61], 0x10388000
	s_mov_b32 s45, 31
	s_branch .LBB0_80
